# v11 + resnorm(sp7) loop: wait+unpack of prefetched rows moved to first consumer
# baseline (speedup 1.0000x reference)
; __device__ __forceinline__ unsigned pk2(float lo, float hi) { const f32x2v v = {lo, hi}; const bf16x2v r = __builtin_convertvector(v, bf16x2v); return __builtin_bit_cast(unsigned, r); }
; __device__ __forceinline__ void rn_proc(RowRegs& R, float* hout32, bf16_t* hout16, bool has_f, float scale, const float4 (&gpo)[4], const float4 (&gpr)[4], bf16_t* a, int row, int lane) {
;   if (has_f) {
;     float fv[4][4]; float ss = 0.f;
; #pragma unroll
;     for (int i = 0; i < 4; ++i) {
;       fv[i][0] = __uint_as_float(R.f[i].x << 16); fv[i][1] = __uint_as_float(R.f[i].x & 0xffff0000u);
;       fv[i][2] = __uint_as_float(R.f[i].y << 16); fv[i][3] = __uint_as_float(R.f[i].y & 0xffff0000u);
;       ss += fv[i][0] * fv[i][0] + fv[i][1] * fv[i][1] + fv[i][2] * fv[i][2] + fv[i][3] * fv[i][3];
;     }
;     ss = wave_sum(ss);
;     const float r = rsqrtf(ss * (1.f / 1024.f) + 1e-6f) * scale;
; #pragma unroll
;     for (int i = 0; i < 4; ++i) { const float4 g = gpo[i];
;       R.h[i].x += fv[i][0] * r * g.x; R.h[i].y += fv[i][1] * r * g.y; R.h[i].z += fv[i][2] * r * g.z; R.h[i].w += fv[i][3] * r * g.w; }
;   }
;   if (hout32) {
; #pragma unroll
;     for (int i = 0; i < 4; ++i) *(float4*)(hout32 + (size_t)row * 1024 + i * 256 + lane * 4) = R.h[i];
;   }
;   if (hout16) {
; #pragma unroll
;     for (int i = 0; i < 4; ++i) { u32x2 o; o.x = pk2(R.h[i].x, R.h[i].y); o.y = pk2(R.h[i].z, R.h[i].w); *(u32x2*)(hout16 + (size_t)row * 1024 + i * 256 + lane * 4) = o; }
;   }
;   if (a) {
;     float ss = 0.f;
; #pragma unroll
;     for (int i = 0; i < 4; ++i) ss += R.h[i].x * R.h[i].x + R.h[i].y * R.h[i].y + R.h[i].z * R.h[i].z + R.h[i].w * R.h[i].w;
;     ss = wave_sum(ss);
.LBB0_129:
	s_or_b64 exec, exec, s[38:39]
	v_and_b32_e32 v143, 0xffff0000, v108
	v_and_b32_e32 v153, 0xffff0000, v102
	v_lshlrev_b32_e32 v142, 16, v108
	v_lshlrev_b32_e32 v152, 16, v102
	v_mov_b32_e32 v160, v143
	v_mov_b32_e32 v161, v153
	v_lshlrev_b32_e32 v86, 16, v109
	v_lshlrev_b32_e32 v150, 16, v103
	v_mov_b32_e32 v158, v142
	v_mov_b32_e32 v159, v152
	v_pk_mul_f32 v[160:161], v[160:161], v[160:161]
	v_mov_b32_e32 v154, v86
	v_mov_b32_e32 v155, v150
	v_pk_fma_f32 v[158:159], v[158:159], v[158:159], v[160:161]
	v_and_b32_e32 v87, 0xffff0000, v109
	v_and_b32_e32 v151, 0xffff0000, v103
	v_pk_fma_f32 v[154:155], v[154:155], v[154:155], v[158:159]
	v_and_b32_e32 v159, 0xffff0000, v100
	v_and_b32_e32 v163, 0xffff0000, v96
	v_mov_b32_e32 v156, v87
	v_mov_b32_e32 v157, v151
	v_lshlrev_b32_e32 v158, 16, v100
	v_lshlrev_b32_e32 v162, 16, v96
	v_mov_b32_e32 v170, v159
	v_mov_b32_e32 v171, v163
	v_pk_fma_f32 v[154:155], v[156:157], v[156:157], v[154:155]
	v_lshlrev_b32_e32 v156, 16, v101
	v_lshlrev_b32_e32 v160, 16, v97
	v_mov_b32_e32 v168, v158
	v_mov_b32_e32 v169, v162
	v_pk_mul_f32 v[170:171], v[170:171], v[170:171]
	v_and_b32_e32 v157, 0xffff0000, v101
	v_and_b32_e32 v161, 0xffff0000, v97
	v_mov_b32_e32 v164, v156
	v_mov_b32_e32 v165, v160
	v_pk_fma_f32 v[168:169], v[168:169], v[168:169], v[170:171]
	v_mov_b32_e32 v166, v157
	v_mov_b32_e32 v167, v161
	v_pk_fma_f32 v[164:165], v[164:165], v[164:165], v[168:169]
	s_mov_b32 s16, 0x800000
	v_pk_fma_f32 v[164:165], v[166:167], v[166:167], v[164:165]
	v_and_b32_e32 v167, 0xffff0000, v88
	v_add_f32_e32 v141, v164, v165
	v_add_f32_e32 v141, v155, v141
	v_add_f32_e32 v141, v154, v141
	ds_bpermute_b32 v154, v144, v141
	v_lshlrev_b32_e32 v166, 16, v88
	v_mov_b32_e32 v175, v167
	v_mov_b32_e32 v173, v166
	s_mul_i32 s17, s92, 24
	s_waitcnt lgkmcnt(0)
	v_add_f32_e32 v141, v141, v154
	ds_bpermute_b32 v154, v145, v141
	s_mov_b32 s38, 0x3a800000
	v_lshlrev_b64 v[138:139], 11, v[138:139]
	v_lshlrev_b64 v[136:137], 11, v[136:137]
	s_waitcnt lgkmcnt(0)
	v_add_f32_e32 v141, v141, v154
	ds_bpermute_b32 v154, v146, v141
	s_waitcnt lgkmcnt(0)
	v_add_f32_e32 v141, v141, v154
	ds_bpermute_b32 v154, v147, v141
	s_waitcnt lgkmcnt(0)
	v_add_f32_e32 v141, v141, v154
	ds_bpermute_b32 v154, v148, v141
	s_waitcnt lgkmcnt(0)
	v_add_f32_e32 v141, v141, v154
	ds_bpermute_b32 v154, v149, v141
	s_waitcnt lgkmcnt(0)
	v_add_f32_e32 v141, v141, v154
	v_fmamk_f32 v141, v141, 0x3a800000, v178
	v_mul_f32_e32 v154, 0x4b800000, v141
	v_cmp_gt_f32_e32 vcc, s16, v141
	s_nop 1
	v_cndmask_b32_e32 v141, v141, v154, vcc
	v_rsq_f32_e32 v141, v141
	s_nop 0
	v_mul_f32_e32 v154, 0x45800000, v141
	v_cndmask_b32_e32 v154, v141, v154, vcc
	v_pk_mul_f32 v[162:163], v[154:155], v[162:163] op_sel_hi:[0,1]
	v_pk_mul_f32 v[158:159], v[154:155], v[158:159] op_sel_hi:[0,1]
	v_pk_fma_f32 v[98:99], v[0:1], v[162:163], v[98:99]
	v_pk_fma_f32 v[110:111], v[8:9], v[158:159], v[110:111]
	v_pk_mul_f32 v[142:143], v[154:155], v[142:143] op_sel_hi:[0,1]
	v_pk_mul_f32 v[160:161], v[154:155], v[160:161] op_sel_hi:[0,1]
	v_pk_mul_f32 v[156:157], v[154:155], v[156:157] op_sel_hi:[0,1]
	v_pk_fma_f32 v[126:127], v[20:21], v[142:143], v[126:127]
	v_pk_mul_f32 v[86:87], v[154:155], v[86:87] op_sel_hi:[0,1]
	v_mov_b32_e32 v142, v111
	v_mov_b32_e32 v143, v99
	v_pk_fma_f32 v[104:105], v[2:3], v[160:161], v[104:105]
	v_pk_fma_f32 v[114:115], v[10:11], v[156:157], v[114:115]
	v_pk_mul_f32 v[152:153], v[154:155], v[152:153] op_sel_hi:[0,1]
	v_pk_fma_f32 v[130:131], v[22:23], v[86:87], v[130:131]
	v_mov_b32_e32 v86, v110
	v_mov_b32_e32 v87, v98
	v_pk_mul_f32 v[142:143], v[142:143], v[142:143]
	v_pk_fma_f32 v[118:119], v[12:13], v[152:153], v[118:119]
	v_pk_mul_f32 v[150:151], v[154:155], v[150:151] op_sel_hi:[0,1]
	v_pk_fma_f32 v[86:87], v[86:87], v[86:87], v[142:143]
	v_mov_b32_e32 v142, v114
	v_mov_b32_e32 v143, v104
	v_pk_fma_f32 v[122:123], v[14:15], v[150:151], v[122:123]
	v_pk_fma_f32 v[86:87], v[142:143], v[142:143], v[86:87]
	v_mov_b32_e32 v142, v115
	v_mov_b32_e32 v143, v105
	v_mov_b32_e32 v150, v127
	v_mov_b32_e32 v151, v119
	v_pk_fma_f32 v[86:87], v[142:143], v[142:143], v[86:87]
	v_mov_b32_e32 v142, v126
	v_mov_b32_e32 v143, v118
	v_pk_mul_f32 v[150:151], v[150:151], v[150:151]
	v_and_b32_e32 v153, 0xffff0000, v94
	v_pk_fma_f32 v[142:143], v[142:143], v[142:143], v[150:151]
	v_mov_b32_e32 v150, v130
	v_mov_b32_e32 v151, v122
	v_and_b32_e32 v157, 0xffff0000, v92
	v_pk_fma_f32 v[142:143], v[150:151], v[150:151], v[142:143]
	v_mov_b32_e32 v150, v131
	v_mov_b32_e32 v151, v123
	v_lshlrev_b32_e32 v152, 16, v94
	v_lshlrev_b32_e32 v156, 16, v92
	v_mov_b32_e32 v164, v153
	v_mov_b32_e32 v165, v157
	v_pk_fma_f32 v[142:143], v[150:151], v[150:151], v[142:143]
	v_lshlrev_b32_e32 v150, 16, v95
	v_lshlrev_b32_e32 v154, 16, v93
	v_mov_b32_e32 v162, v152
	v_mov_b32_e32 v163, v156
	v_pk_mul_f32 v[164:165], v[164:165], v[164:165]
	v_mov_b32_e32 v158, v150
	v_mov_b32_e32 v159, v154
	v_pk_fma_f32 v[162:163], v[162:163], v[162:163], v[164:165]
	v_and_b32_e32 v151, 0xffff0000, v95
	v_and_b32_e32 v155, 0xffff0000, v93
	v_pk_fma_f32 v[158:159], v[158:159], v[158:159], v[162:163]
	v_and_b32_e32 v163, 0xffff0000, v90
	v_mov_b32_e32 v160, v151
	v_mov_b32_e32 v161, v155
	v_lshlrev_b32_e32 v162, 16, v90
	v_mov_b32_e32 v174, v163
	v_pk_fma_f32 v[158:159], v[160:161], v[160:161], v[158:159]
	v_lshlrev_b32_e32 v160, 16, v91
	v_lshlrev_b32_e32 v164, 16, v89
	v_mov_b32_e32 v172, v162
	v_pk_mul_f32 v[174:175], v[174:175], v[174:175]
	v_and_b32_e32 v161, 0xffff0000, v91
	v_and_b32_e32 v165, 0xffff0000, v89
	v_mov_b32_e32 v168, v160
	v_mov_b32_e32 v169, v164
	v_pk_fma_f32 v[172:173], v[172:173], v[172:173], v[174:175]
	v_mov_b32_e32 v170, v161
	v_mov_b32_e32 v171, v165
	v_pk_fma_f32 v[168:169], v[168:169], v[168:169], v[172:173]
	s_nop 0
	v_pk_fma_f32 v[168:169], v[170:171], v[170:171], v[168:169]
	v_mov_b32_e32 v171, v86
	v_mov_b32_e32 v170, v168
	v_mov_b32_e32 v86, v169
	v_pk_add_f32 v[86:87], v[170:171], v[86:87]
	v_mov_b32_e32 v168, v159
	v_mov_b32_e32 v169, v143
	v_pk_add_f32 v[86:87], v[168:169], v[86:87]
	v_mov_b32_e32 v159, v142
	v_pk_add_f32 v[86:87], v[158:159], v[86:87]
	ds_bpermute_b32 v143, v144, v87
	ds_bpermute_b32 v142, v144, v86
	v_cvt_pk_bf16_f32 v168, v98, v99
	v_cvt_pk_bf16_f32 v169, v104, v105
	s_waitcnt lgkmcnt(0)
; __device__ __forceinline__ unsigned pk2(float lo, float hi) { const f32x2v v = {lo, hi}; const bf16x2v r = __builtin_convertvector(v, bf16x2v); return __builtin_bit_cast(unsigned, r); }
; __device__ __forceinline__ void rn_proc(RowRegs& R, float* hout32, bf16_t* hout16, bool has_f, float scale, const float4 (&gpo)[4], const float4 (&gpr)[4], bf16_t* a, int row, int lane) {
;     ...
;   if (hout32) {
; #pragma unroll
;     for (int i = 0; i < 4; ++i) *(float4*)(hout32 + (size_t)row * 1024 + i * 256 + lane * 4) = R.h[i];
;   }
;   if (hout16) {
; #pragma unroll
;     for (int i = 0; i < 4; ++i) { u32x2 o; o.x = pk2(R.h[i].x, R.h[i].y); o.y = pk2(R.h[i].z, R.h[i].w); *(u32x2*)(hout16 + (size_t)row * 1024 + i * 256 + lane * 4) = o; }
;   }
;   if (a) {
;     float ss = 0.f;
; #pragma unroll
;     for (int i = 0; i < 4; ++i) ss += R.h[i].x * R.h[i].x + R.h[i].y * R.h[i].y + R.h[i].z * R.h[i].z + R.h[i].w * R.h[i].w;
;     ss = wave_sum(ss);
;     const float r = rsqrtf(ss * (1.f / 1024.f) + 1e-6f);
; #pragma unroll
;     for (int i = 0; i < 4; ++i) { const float4 g = gpr[i];
;       u32x2 o; o.x = pk2(R.h[i].x * r * g.x, R.h[i].y * r * g.y); o.y = pk2(R.h[i].z * r * g.z, R.h[i].w * r * g.w);
;       *(u32x2*)(a + (size_t)row * 1024 + i * 256 + lane * 4) = o; }
	v_pk_add_f32 v[86:87], v[86:87], v[142:143]
	ds_bpermute_b32 v143, v145, v87
	ds_bpermute_b32 v142, v145, v86
	s_waitcnt lgkmcnt(0)
	v_pk_add_f32 v[142:143], v[86:87], v[142:143]
	ds_bpermute_b32 v159, v146, v143
	ds_bpermute_b32 v158, v146, v142
	v_add_u32_e32 v86, s17, v140
	s_waitcnt lgkmcnt(0)
	v_pk_add_f32 v[140:141], v[142:143], v[158:159]
	ds_bpermute_b32 v143, v147, v141
	ds_bpermute_b32 v142, v147, v140
	v_lshl_add_u64 v[158:159], v[64:65], 0, v[138:139]
	global_store_dwordx2 v[158:159], v[168:169], off
	v_cvt_pk_bf16_f32 v168, v110, v111
	v_cvt_pk_bf16_f32 v169, v114, v115
	s_waitcnt lgkmcnt(0)
	v_pk_add_f32 v[140:141], v[140:141], v[142:143]
	ds_bpermute_b32 v143, v148, v141
	ds_bpermute_b32 v142, v148, v140
	global_store_dwordx2 v[158:159], v[168:169], off offset:512
	v_cvt_pk_bf16_f32 v168, v118, v119
	v_cvt_pk_bf16_f32 v169, v122, v123
	global_store_dwordx2 v[158:159], v[168:169], off offset:1024
	s_waitcnt lgkmcnt(0)
	v_pk_add_f32 v[140:141], v[140:141], v[142:143]
	ds_bpermute_b32 v143, v149, v141
	ds_bpermute_b32 v142, v149, v140
	v_cvt_pk_bf16_f32 v168, v126, v127
	v_cvt_pk_bf16_f32 v169, v130, v131
	global_store_dwordx2 v[158:159], v[168:169], off offset:1536
	v_lshl_add_u64 v[138:139], v[68:69], 0, v[138:139]
	s_waitcnt lgkmcnt(0)
	v_pk_add_f32 v[140:141], v[140:141], v[142:143]
	s_nop 0
	v_pk_fma_f32 v[140:141], v[140:141], s[38:39], v[178:179] op_sel_hi:[1,0,0]
	s_nop 0
	v_mul_f32_e32 v87, 0x4b800000, v141
	v_cmp_gt_f32_e32 vcc, s16, v141
	s_nop 1
	v_cndmask_b32_e32 v87, v141, v87, vcc
	v_rsq_f32_e32 v87, v87
	s_nop 0
	v_mul_f32_e32 v141, 0x45800000, v87
	v_cndmask_b32_e32 v142, v87, v141, vcc
	v_mul_f32_e32 v87, 0x4b800000, v140
	v_cmp_gt_f32_e32 vcc, s16, v140
	v_pk_mul_f32 v[158:159], v[98:99], v[142:143] op_sel_hi:[1,0]
	v_pk_mul_f32 v[168:169], v[104:105], v[142:143] op_sel_hi:[1,0]
	v_cndmask_b32_e32 v87, v140, v87, vcc
	v_pk_mul_f32 v[158:159], v[4:5], v[158:159]
	v_pk_mul_f32 v[168:169], v[6:7], v[168:169]
	v_rsq_f32_e32 v87, v87
	v_cvt_pk_bf16_f32 v158, v158, v159
	v_cvt_pk_bf16_f32 v159, v168, v169
	global_store_dwordx2 v[138:139], v[158:159], off
	v_pk_mul_f32 v[158:159], v[110:111], v[142:143] op_sel_hi:[1,0]
	v_pk_mul_f32 v[168:169], v[114:115], v[142:143] op_sel_hi:[1,0]
	v_pk_mul_f32 v[158:159], v[16:17], v[158:159]
	v_pk_mul_f32 v[168:169], v[18:19], v[168:169]
	v_cvt_pk_bf16_f32 v158, v158, v159
	v_cvt_pk_bf16_f32 v159, v168, v169
	v_pk_mul_f32 v[140:141], v[118:119], v[142:143] op_sel_hi:[1,0]
	v_mul_f32_e32 v143, 0x45800000, v87
	global_store_dwordx2 v[138:139], v[158:159], off offset:512
	v_cndmask_b32_e32 v158, v87, v143, vcc
	v_pk_mul_f32 v[166:167], v[158:159], v[166:167] op_sel_hi:[0,1]
	v_pk_mul_f32 v[162:163], v[158:159], v[162:163] op_sel_hi:[0,1]
	v_pk_fma_f32 v[106:107], v[0:1], v[166:167], v[106:107]
	v_pk_fma_f32 v[116:117], v[8:9], v[162:163], v[116:117]
	v_pk_mul_f32 v[152:153], v[158:159], v[152:153] op_sel_hi:[0,1]
	v_pk_mul_f32 v[164:165], v[158:159], v[164:165] op_sel_hi:[0,1]
	v_pk_mul_f32 v[160:161], v[158:159], v[160:161] op_sel_hi:[0,1]
	v_pk_fma_f32 v[132:133], v[20:21], v[152:153], v[132:133]
	v_pk_mul_f32 v[150:151], v[158:159], v[150:151] op_sel_hi:[0,1]
	v_mov_b32_e32 v152, v117
	v_mov_b32_e32 v153, v107
	v_pk_fma_f32 v[112:113], v[2:3], v[164:165], v[112:113]
	v_pk_fma_f32 v[120:121], v[10:11], v[160:161], v[120:121]
	v_pk_mul_f32 v[156:157], v[158:159], v[156:157] op_sel_hi:[0,1]
	v_pk_fma_f32 v[134:135], v[22:23], v[150:151], v[134:135]
	v_mov_b32_e32 v150, v116
	v_mov_b32_e32 v151, v106
	v_pk_mul_f32 v[152:153], v[152:153], v[152:153]
	v_pk_fma_f32 v[124:125], v[12:13], v[156:157], v[124:125]
	v_pk_mul_f32 v[154:155], v[158:159], v[154:155] op_sel_hi:[0,1]
	v_pk_fma_f32 v[150:151], v[150:151], v[150:151], v[152:153]
	v_mov_b32_e32 v152, v120
	v_mov_b32_e32 v153, v112
	v_pk_fma_f32 v[128:129], v[14:15], v[154:155], v[128:129]
	v_pk_fma_f32 v[150:151], v[152:153], v[152:153], v[150:151]
	v_mov_b32_e32 v152, v121
	v_mov_b32_e32 v153, v113
	v_mov_b32_e32 v154, v133
	v_mov_b32_e32 v155, v125
	v_pk_fma_f32 v[150:151], v[152:153], v[152:153], v[150:151]
	v_mov_b32_e32 v152, v132
	v_mov_b32_e32 v153, v124
	v_pk_mul_f32 v[154:155], v[154:155], v[154:155]
	v_add_f32_e32 v87, v150, v151
	v_pk_fma_f32 v[152:153], v[152:153], v[152:153], v[154:155]
	v_mov_b32_e32 v154, v134
	v_mov_b32_e32 v155, v128
	v_pk_fma_f32 v[152:153], v[154:155], v[154:155], v[152:153]
	v_mov_b32_e32 v154, v135
	v_mov_b32_e32 v155, v129
	v_pk_fma_f32 v[152:153], v[154:155], v[154:155], v[152:153]
	v_pk_mul_f32 v[140:141], v[24:25], v[140:141]
	v_add_f32_e32 v87, v153, v87
	v_add_f32_e32 v87, v152, v87
	ds_bpermute_b32 v143, v144, v87
	v_cvt_pk_bf16_f32 v140, v140, v141
	s_waitcnt lgkmcnt(0)
; __device__ __forceinline__ unsigned pk2(float lo, float hi) { const f32x2v v = {lo, hi}; const bf16x2v r = __builtin_convertvector(v, bf16x2v); return __builtin_bit_cast(unsigned, r); }
; __device__ __forceinline__ void rn_load(RowRegs& R, const float* hin32, const bf16_t* hin16, const bf16_t* f, int row, int lane) {
;     ...
;     for (int i = 0; i < 4; ++i) { const u32x2 v = *(const u32x2*)(hin16 + (size_t)row * 1024 + i * 256 + lane * 4);
;       R.h[i].x = __uint_as_float(v.x << 16); R.h[i].y = __uint_as_float(v.x & 0xffff0000u); R.h[i].z = __uint_as_float(v.y << 16); R.h[i].w = __uint_as_float(v.y & 0xffff0000u); }
; __device__ __forceinline__ void rn_proc(RowRegs& R, float* hout32, bf16_t* hout16, bool has_f, float scale, const float4 (&gpo)[4], const float4 (&gpr)[4], bf16_t* a, int row, int lane) {
;     ...
;   if (a) {
;     float ss = 0.f;
; #pragma unroll
;     for (int i = 0; i < 4; ++i) ss += R.h[i].x * R.h[i].x + R.h[i].y * R.h[i].y + R.h[i].z * R.h[i].z + R.h[i].w * R.h[i].w;
;     ss = wave_sum(ss);
;     const float r = rsqrtf(ss * (1.f / 1024.f) + 1e-6f);
; #pragma unroll
;     for (int i = 0; i < 4; ++i) { const float4 g = gpr[i];
;       u32x2 o; o.x = pk2(R.h[i].x * r * g.x, R.h[i].y * r * g.y); o.y = pk2(R.h[i].z * r * g.z, R.h[i].w * r * g.w);
;       *(u32x2*)(a + (size_t)row * 1024 + i * 256 + lane * 4) = o; }
	v_add_f32_e32 v87, v87, v143
	v_pk_mul_f32 v[150:151], v[122:123], v[142:143] op_sel_hi:[1,0]
	ds_bpermute_b32 v143, v145, v87
	v_pk_mul_f32 v[150:151], v[26:27], v[150:151]
	s_waitcnt lgkmcnt(0)
	v_add_f32_e32 v87, v87, v143
	v_cvt_pk_bf16_f32 v141, v150, v151
	ds_bpermute_b32 v150, v146, v87
	global_store_dwordx2 v[138:139], v[140:141], off offset:1024
	v_pk_mul_f32 v[140:141], v[126:127], v[142:143] op_sel_hi:[1,0]
	v_pk_mul_f32 v[142:143], v[130:131], v[142:143] op_sel_hi:[1,0]
	v_pk_mul_f32 v[140:141], v[28:29], v[140:141]
	v_pk_mul_f32 v[142:143], v[30:31], v[142:143]
	s_waitcnt lgkmcnt(0)
	v_add_f32_e32 v87, v87, v150
	v_cvt_pk_bf16_f32 v140, v140, v141
	v_cvt_pk_bf16_f32 v141, v142, v143
	ds_bpermute_b32 v142, v147, v87
	global_store_dwordx2 v[138:139], v[140:141], off offset:1536
	v_lshl_add_u64 v[138:139], v[64:65], 0, v[136:137]
	v_cvt_pk_bf16_f32 v140, v106, v107
	v_cvt_pk_bf16_f32 v141, v112, v113
	s_waitcnt lgkmcnt(0)
	v_add_f32_e32 v87, v87, v142
	ds_bpermute_b32 v142, v148, v87
	global_store_dwordx2 v[138:139], v[140:141], off
	v_cvt_pk_bf16_f32 v140, v116, v117
	v_cvt_pk_bf16_f32 v141, v120, v121
	global_store_dwordx2 v[138:139], v[140:141], off offset:512
	s_waitcnt lgkmcnt(0)
	v_add_f32_e32 v87, v87, v142
	ds_bpermute_b32 v142, v149, v87
	v_cvt_pk_bf16_f32 v140, v124, v125
	v_cvt_pk_bf16_f32 v141, v128, v129
	global_store_dwordx2 v[138:139], v[140:141], off offset:1024
	v_cvt_pk_bf16_f32 v141, v134, v135
	s_waitcnt lgkmcnt(0)
	v_add_f32_e32 v87, v87, v142
	v_fmamk_f32 v87, v87, 0x3a800000, v178
	v_mul_f32_e32 v140, 0x4b800000, v87
	v_cmp_gt_f32_e32 vcc, s16, v87
	v_lshl_add_u64 v[136:137], v[68:69], 0, v[136:137]
	s_nop 0
	v_cndmask_b32_e32 v87, v87, v140, vcc
	v_rsq_f32_e32 v87, v87
	v_cvt_pk_bf16_f32 v140, v132, v133
	global_store_dwordx2 v[138:139], v[140:141], off offset:1536
	v_mul_f32_e32 v138, 0x45800000, v87
	v_cndmask_b32_e32 v138, v87, v138, vcc
	v_pk_mul_f32 v[140:141], v[106:107], v[138:139] op_sel_hi:[1,0]
	v_pk_mul_f32 v[142:143], v[112:113], v[138:139] op_sel_hi:[1,0]
	v_pk_mul_f32 v[140:141], v[4:5], v[140:141]
	v_pk_mul_f32 v[142:143], v[6:7], v[142:143]
	v_cvt_pk_bf16_f32 v140, v140, v141
	v_cvt_pk_bf16_f32 v141, v142, v143
	global_store_dwordx2 v[136:137], v[140:141], off
	v_pk_mul_f32 v[140:141], v[116:117], v[138:139] op_sel_hi:[1,0]
	v_pk_mul_f32 v[142:143], v[120:121], v[138:139] op_sel_hi:[1,0]
	v_pk_mul_f32 v[140:141], v[16:17], v[140:141]
	v_pk_mul_f32 v[142:143], v[18:19], v[142:143]
	v_cvt_pk_bf16_f32 v140, v140, v141
	v_cvt_pk_bf16_f32 v141, v142, v143
	global_store_dwordx2 v[136:137], v[140:141], off offset:512
	v_pk_mul_f32 v[140:141], v[124:125], v[138:139] op_sel_hi:[1,0]
	v_pk_mul_f32 v[142:143], v[128:129], v[138:139] op_sel_hi:[1,0]
	v_pk_mul_f32 v[140:141], v[24:25], v[140:141]
	v_pk_mul_f32 v[142:143], v[26:27], v[142:143]
	v_cvt_pk_bf16_f32 v140, v140, v141
	v_cvt_pk_bf16_f32 v141, v142, v143
	global_store_dwordx2 v[136:137], v[140:141], off offset:1024
	v_pk_mul_f32 v[140:141], v[132:133], v[138:139] op_sel_hi:[1,0]
	v_pk_mul_f32 v[138:139], v[134:135], v[138:139] op_sel_hi:[1,0]
	v_pk_mul_f32 v[140:141], v[28:29], v[140:141]
	v_pk_mul_f32 v[138:139], v[30:31], v[138:139]
	v_cmp_lt_i32_e32 vcc, s60, v86
	v_cvt_pk_bf16_f32 v140, v140, v141
	v_cvt_pk_bf16_f32 v141, v138, v139
	s_orn2_b64 s[38:39], vcc, exec
	global_store_dwordx2 v[136:137], v[140:141], off offset:1536
	s_waitcnt vmcnt(16)
	v_lshlrev_b32_e32 v48, 16, v50
	v_and_b32_e32 v49, 0xffff0000, v50
	v_lshlrev_b32_e32 v50, 16, v51
	v_and_b32_e32 v51, 0xffff0000, v51
	v_lshlrev_b32_e32 v52, 16, v54
	v_and_b32_e32 v53, 0xffff0000, v54
	v_lshlrev_b32_e32 v54, 16, v55
	v_and_b32_e32 v55, 0xffff0000, v55
	v_lshlrev_b32_e32 v56, 16, v58
	v_and_b32_e32 v57, 0xffff0000, v58
	v_lshlrev_b32_e32 v58, 16, v59
	v_and_b32_e32 v59, 0xffff0000, v59
	v_lshlrev_b32_e32 v60, 16, v62
	v_and_b32_e32 v61, 0xffff0000, v62
	v_lshlrev_b32_e32 v62, 16, v63
	v_and_b32_e32 v63, 0xffff0000, v63
	v_lshlrev_b32_e32 v70, 16, v72
	v_and_b32_e32 v71, 0xffff0000, v72
	v_lshlrev_b32_e32 v72, 16, v73
	v_and_b32_e32 v73, 0xffff0000, v73
	v_lshlrev_b32_e32 v74, 16, v76
	v_and_b32_e32 v75, 0xffff0000, v76
	v_lshlrev_b32_e32 v76, 16, v77
	v_and_b32_e32 v77, 0xffff0000, v77
	v_lshlrev_b32_e32 v78, 16, v80
	v_and_b32_e32 v79, 0xffff0000, v80
	v_lshlrev_b32_e32 v80, 16, v81
	v_and_b32_e32 v81, 0xffff0000, v81
	v_lshlrev_b32_e32 v82, 16, v84
	v_and_b32_e32 v83, 0xffff0000, v84
	v_lshlrev_b32_e32 v84, 16, v85
	v_and_b32_e32 v85, 0xffff0000, v85

; __device__ __forceinline__ unsigned pk2(float lo, float hi) { const f32x2v v = {lo, hi}; const bf16x2v r = __builtin_convertvector(v, bf16x2v); return __builtin_bit_cast(unsigned, r); }
; __device__ __forceinline__ void rn_proc(RowRegs& R, float* hout32, bf16_t* hout16, bool has_f, float scale, const float4 (&gpo)[4], const float4 (&gpr)[4], bf16_t* a, int row, int lane) {
;   if (has_f) {
;     float fv[4][4]; float ss = 0.f;
; #pragma unroll
;     for (int i = 0; i < 4; ++i) {
;       fv[i][0] = __uint_as_float(R.f[i].x << 16); fv[i][1] = __uint_as_float(R.f[i].x & 0xffff0000u);
;       fv[i][2] = __uint_as_float(R.f[i].y << 16); fv[i][3] = __uint_as_float(R.f[i].y & 0xffff0000u);
;       ss += fv[i][0] * fv[i][0] + fv[i][1] * fv[i][1] + fv[i][2] * fv[i][2] + fv[i][3] * fv[i][3];
;     }
;     ss = wave_sum(ss);
;     const float r = rsqrtf(ss * (1.f / 1024.f) + 1e-6f) * scale;
; #pragma unroll
;     for (int i = 0; i < 4; ++i) { const float4 g = gpo[i];
;       R.h[i].x += fv[i][0] * r * g.x; R.h[i].y += fv[i][1] * r * g.y; R.h[i].z += fv[i][2] * r * g.z; R.h[i].w += fv[i][3] * r * g.w; }
;   }
;   if (hout32) {
; #pragma unroll
;     for (int i = 0; i < 4; ++i) *(float4*)(hout32 + (size_t)row * 1024 + i * 256 + lane * 4) = R.h[i];
;   }
;   if (hout16) {
; #pragma unroll
;     for (int i = 0; i < 4; ++i) { u32x2 o; o.x = pk2(R.h[i].x, R.h[i].y); o.y = pk2(R.h[i].z, R.h[i].w); *(u32x2*)(hout16 + (size_t)row * 1024 + i * 256 + lane * 4) = o; }
;   }
;   if (a) {
;     float ss = 0.f;
; #pragma unroll
;     for (int i = 0; i < 4; ++i) ss += R.h[i].x * R.h[i].x + R.h[i].y * R.h[i].y + R.h[i].z * R.h[i].z + R.h[i].w * R.h[i].w;
;     ss = wave_sum(ss);
.LBB0_133:
	s_or_b64 exec, exec, s[30:31]
	v_and_b32_e32 v143, 0xffff0000, v38
	v_and_b32_e32 v153, 0xffff0000, v36
	v_lshlrev_b32_e32 v142, 16, v38
	v_lshlrev_b32_e32 v152, 16, v36
	v_mov_b32_e32 v160, v143
	v_mov_b32_e32 v161, v153
	v_lshlrev_b32_e32 v140, 16, v39
	v_lshlrev_b32_e32 v150, 16, v37
	v_mov_b32_e32 v158, v142
	v_mov_b32_e32 v159, v152
	v_pk_mul_f32 v[160:161], v[160:161], v[160:161]
	v_mov_b32_e32 v154, v140
	v_mov_b32_e32 v155, v150
	v_pk_fma_f32 v[158:159], v[158:159], v[158:159], v[160:161]
	v_and_b32_e32 v141, 0xffff0000, v39
	v_and_b32_e32 v151, 0xffff0000, v37
	v_pk_fma_f32 v[154:155], v[154:155], v[154:155], v[158:159]
	v_and_b32_e32 v159, 0xffff0000, v34
	v_and_b32_e32 v163, 0xffff0000, v32
	v_mov_b32_e32 v156, v141
	v_mov_b32_e32 v157, v151
	v_lshlrev_b32_e32 v158, 16, v34
	v_lshlrev_b32_e32 v162, 16, v32
	v_mov_b32_e32 v170, v163
	v_mov_b32_e32 v171, v159
	v_pk_fma_f32 v[154:155], v[156:157], v[156:157], v[154:155]
	v_lshlrev_b32_e32 v156, 16, v35
	v_lshlrev_b32_e32 v160, 16, v33
	v_mov_b32_e32 v168, v162
	v_mov_b32_e32 v169, v158
	v_pk_mul_f32 v[170:171], v[170:171], v[170:171]
	v_and_b32_e32 v157, 0xffff0000, v35
	v_and_b32_e32 v161, 0xffff0000, v33
	v_mov_b32_e32 v164, v160
	v_mov_b32_e32 v165, v156
	v_pk_fma_f32 v[168:169], v[168:169], v[168:169], v[170:171]
	v_mov_b32_e32 v166, v161
	v_mov_b32_e32 v167, v157
	v_pk_fma_f32 v[164:165], v[164:165], v[164:165], v[168:169]
	s_mov_b32 s17, 0x800000
	v_pk_fma_f32 v[164:165], v[166:167], v[166:167], v[164:165]
	v_and_b32_e32 v167, 0xffff0000, v40
	v_add_f32_e32 v87, v164, v165
	v_add_f32_e32 v87, v155, v87
	v_add_f32_e32 v87, v154, v87
	ds_bpermute_b32 v154, v144, v87
	v_lshlrev_b32_e32 v166, 16, v40
	v_mov_b32_e32 v174, v167
	v_mov_b32_e32 v172, v166
	s_mov_b32 s16, 0x3a800000
	s_waitcnt lgkmcnt(0)
	v_add_f32_e32 v87, v87, v154
	ds_bpermute_b32 v154, v145, v87
	s_mov_b64 s[38:39], -1
	s_waitcnt lgkmcnt(0)
	v_add_f32_e32 v87, v87, v154
	ds_bpermute_b32 v154, v146, v87
	s_waitcnt lgkmcnt(0)
	v_add_f32_e32 v87, v87, v154
	ds_bpermute_b32 v154, v147, v87
	s_waitcnt lgkmcnt(0)
	v_add_f32_e32 v87, v87, v154
	ds_bpermute_b32 v154, v148, v87
	s_waitcnt lgkmcnt(0)
	v_add_f32_e32 v87, v87, v154
	ds_bpermute_b32 v154, v149, v87
	s_waitcnt lgkmcnt(0)
	v_add_f32_e32 v87, v87, v154
	v_fmamk_f32 v87, v87, 0x3a800000, v178
	v_mul_f32_e32 v154, 0x4b800000, v87
	v_cmp_gt_f32_e32 vcc, s17, v87
	s_nop 1
	v_cndmask_b32_e32 v87, v87, v154, vcc
	v_rsq_f32_e32 v87, v87
	s_nop 0
	v_mul_f32_e32 v154, 0x45800000, v87
	v_cndmask_b32_e32 v154, v87, v154, vcc
	v_pk_mul_f32 v[162:163], v[154:155], v[162:163] op_sel_hi:[0,1]
	v_pk_mul_f32 v[158:159], v[154:155], v[158:159] op_sel_hi:[0,1]
	v_pk_fma_f32 v[48:49], v[0:1], v[162:163], v[48:49]
	v_pk_fma_f32 v[52:53], v[8:9], v[158:159], v[52:53]
	v_pk_mul_f32 v[142:143], v[154:155], v[142:143] op_sel_hi:[0,1]
	v_pk_mul_f32 v[160:161], v[154:155], v[160:161] op_sel_hi:[0,1]
	v_pk_mul_f32 v[156:157], v[154:155], v[156:157] op_sel_hi:[0,1]
	v_pk_fma_f32 v[60:61], v[20:21], v[142:143], v[60:61]
	v_pk_mul_f32 v[140:141], v[154:155], v[140:141] op_sel_hi:[0,1]
	v_mov_b32_e32 v142, v53
	v_mov_b32_e32 v143, v49
	v_pk_fma_f32 v[50:51], v[2:3], v[160:161], v[50:51]
	v_pk_fma_f32 v[54:55], v[10:11], v[156:157], v[54:55]
	v_pk_mul_f32 v[152:153], v[154:155], v[152:153] op_sel_hi:[0,1]
	v_pk_fma_f32 v[62:63], v[22:23], v[140:141], v[62:63]
	v_mov_b32_e32 v140, v52
	v_mov_b32_e32 v141, v48
	v_pk_mul_f32 v[142:143], v[142:143], v[142:143]
	v_pk_fma_f32 v[56:57], v[12:13], v[152:153], v[56:57]
	v_pk_mul_f32 v[150:151], v[154:155], v[150:151] op_sel_hi:[0,1]
	v_pk_fma_f32 v[140:141], v[140:141], v[140:141], v[142:143]
	v_mov_b32_e32 v142, v54
	v_mov_b32_e32 v143, v50
	v_pk_fma_f32 v[58:59], v[14:15], v[150:151], v[58:59]
	v_pk_fma_f32 v[140:141], v[142:143], v[142:143], v[140:141]
	v_mov_b32_e32 v142, v55
	v_mov_b32_e32 v143, v51
	v_mov_b32_e32 v150, v61
	v_mov_b32_e32 v151, v57
	v_pk_fma_f32 v[140:141], v[142:143], v[142:143], v[140:141]
	v_mov_b32_e32 v142, v60
	v_mov_b32_e32 v143, v56
	v_pk_mul_f32 v[150:151], v[150:151], v[150:151]
	v_and_b32_e32 v153, 0xffff0000, v46
	v_pk_fma_f32 v[142:143], v[142:143], v[142:143], v[150:151]
	v_mov_b32_e32 v150, v62
	v_mov_b32_e32 v151, v58
	v_and_b32_e32 v157, 0xffff0000, v44
	v_pk_fma_f32 v[142:143], v[150:151], v[150:151], v[142:143]
	v_mov_b32_e32 v150, v63
	v_mov_b32_e32 v151, v59
	v_lshlrev_b32_e32 v152, 16, v46
	v_lshlrev_b32_e32 v156, 16, v44
	v_mov_b32_e32 v164, v153
	v_mov_b32_e32 v165, v157
	v_pk_fma_f32 v[142:143], v[150:151], v[150:151], v[142:143]
	v_lshlrev_b32_e32 v150, 16, v47
	v_lshlrev_b32_e32 v154, 16, v45
	v_mov_b32_e32 v162, v152
	v_mov_b32_e32 v163, v156
	v_pk_mul_f32 v[164:165], v[164:165], v[164:165]
	v_mov_b32_e32 v158, v150
	v_mov_b32_e32 v159, v154
	v_pk_fma_f32 v[162:163], v[162:163], v[162:163], v[164:165]
	v_and_b32_e32 v151, 0xffff0000, v47
	v_and_b32_e32 v155, 0xffff0000, v45
	v_pk_fma_f32 v[158:159], v[158:159], v[158:159], v[162:163]
	v_and_b32_e32 v163, 0xffff0000, v42
	v_mov_b32_e32 v160, v151
	v_mov_b32_e32 v161, v155
	v_lshlrev_b32_e32 v162, 16, v42
	v_mov_b32_e32 v175, v163
	v_pk_fma_f32 v[158:159], v[160:161], v[160:161], v[158:159]
	v_lshlrev_b32_e32 v160, 16, v43
	v_lshlrev_b32_e32 v164, 16, v41
	v_mov_b32_e32 v173, v162
	v_pk_mul_f32 v[174:175], v[174:175], v[174:175]
	v_and_b32_e32 v161, 0xffff0000, v43
	v_and_b32_e32 v165, 0xffff0000, v41
	v_mov_b32_e32 v168, v164
	v_mov_b32_e32 v169, v160
	v_pk_fma_f32 v[172:173], v[172:173], v[172:173], v[174:175]
	v_mov_b32_e32 v170, v165
	v_mov_b32_e32 v171, v161
	v_pk_fma_f32 v[168:169], v[168:169], v[168:169], v[172:173]
	v_ashrrev_i32_e32 v87, 31, v86
	v_pk_fma_f32 v[168:169], v[170:171], v[170:171], v[168:169]
	v_mov_b32_e32 v171, v140
	v_mov_b32_e32 v170, v168
	v_mov_b32_e32 v140, v169
	v_pk_add_f32 v[140:141], v[170:171], v[140:141]
	v_mov_b32_e32 v168, v159
	v_mov_b32_e32 v169, v143
	v_pk_add_f32 v[140:141], v[168:169], v[140:141]
	v_mov_b32_e32 v159, v142
	v_pk_add_f32 v[140:141], v[158:159], v[140:141]
	ds_bpermute_b32 v143, v144, v141
	ds_bpermute_b32 v142, v144, v140
	v_lshlrev_b64 v[158:159], 11, v[86:87]
	v_lshl_add_u64 v[168:169], v[64:65], 0, v[158:159]
	v_cvt_pk_bf16_f32 v170, v48, v49
	v_cvt_pk_bf16_f32 v171, v50, v51
	s_waitcnt lgkmcnt(0)
; __device__ __forceinline__ unsigned pk2(float lo, float hi) { const f32x2v v = {lo, hi}; const bf16x2v r = __builtin_convertvector(v, bf16x2v); return __builtin_bit_cast(unsigned, r); }
; __device__ __forceinline__ void rn_proc(RowRegs& R, float* hout32, bf16_t* hout16, bool has_f, float scale, const float4 (&gpo)[4], const float4 (&gpr)[4], bf16_t* a, int row, int lane) {
;     ...
;   if (hout32) {
; #pragma unroll
;     for (int i = 0; i < 4; ++i) *(float4*)(hout32 + (size_t)row * 1024 + i * 256 + lane * 4) = R.h[i];
;   }
;   if (hout16) {
; #pragma unroll
;     for (int i = 0; i < 4; ++i) { u32x2 o; o.x = pk2(R.h[i].x, R.h[i].y); o.y = pk2(R.h[i].z, R.h[i].w); *(u32x2*)(hout16 + (size_t)row * 1024 + i * 256 + lane * 4) = o; }
;   }
;   if (a) {
;     float ss = 0.f;
; #pragma unroll
;     for (int i = 0; i < 4; ++i) ss += R.h[i].x * R.h[i].x + R.h[i].y * R.h[i].y + R.h[i].z * R.h[i].z + R.h[i].w * R.h[i].w;
;     ss = wave_sum(ss);
;     const float r = rsqrtf(ss * (1.f / 1024.f) + 1e-6f);
; #pragma unroll
;     for (int i = 0; i < 4; ++i) { const float4 g = gpr[i];
;       u32x2 o; o.x = pk2(R.h[i].x * r * g.x, R.h[i].y * r * g.y); o.y = pk2(R.h[i].z * r * g.z, R.h[i].w * r * g.w);
;       *(u32x2*)(a + (size_t)row * 1024 + i * 256 + lane * 4) = o; }
	v_pk_add_f32 v[140:141], v[140:141], v[142:143]
	ds_bpermute_b32 v143, v145, v141
	ds_bpermute_b32 v142, v145, v140
	global_store_dwordx2 v[168:169], v[170:171], off
	v_cvt_pk_bf16_f32 v170, v52, v53
	v_cvt_pk_bf16_f32 v171, v54, v55
	global_store_dwordx2 v[168:169], v[170:171], off offset:512
	s_waitcnt lgkmcnt(0)
	v_pk_add_f32 v[140:141], v[140:141], v[142:143]
	ds_bpermute_b32 v143, v146, v141
	ds_bpermute_b32 v142, v146, v140
	v_cvt_pk_bf16_f32 v170, v56, v57
	v_cvt_pk_bf16_f32 v171, v58, v59
	global_store_dwordx2 v[168:169], v[170:171], off offset:1024
	v_cvt_pk_bf16_f32 v170, v60, v61
	s_waitcnt lgkmcnt(0)
	v_pk_add_f32 v[140:141], v[140:141], v[142:143]
	ds_bpermute_b32 v143, v147, v141
	ds_bpermute_b32 v142, v147, v140
	v_cvt_pk_bf16_f32 v171, v62, v63
	global_store_dwordx2 v[168:169], v[170:171], off offset:1536
	v_lshl_add_u64 v[158:159], v[68:69], 0, v[158:159]
	s_waitcnt lgkmcnt(0)
	v_pk_add_f32 v[140:141], v[140:141], v[142:143]
	ds_bpermute_b32 v143, v148, v141
	ds_bpermute_b32 v142, v148, v140
	s_waitcnt lgkmcnt(0)
	v_pk_add_f32 v[140:141], v[140:141], v[142:143]
	ds_bpermute_b32 v143, v149, v141
	ds_bpermute_b32 v142, v149, v140
	s_waitcnt lgkmcnt(0)
	v_pk_add_f32 v[140:141], v[140:141], v[142:143]
	s_nop 0
	v_pk_fma_f32 v[142:143], v[140:141], s[16:17], v[178:179] op_sel_hi:[1,0,0]
	v_readlane_b32 s16, v252, 51
	v_mul_f32_e32 v87, 0x4b800000, v143
	v_cmp_gt_f32_e32 vcc, s17, v143
	v_add_u32_e32 v140, s16, v86
	s_mov_b32 s16, 0x8000
	v_cndmask_b32_e32 v87, v143, v87, vcc
	v_rsq_f32_e32 v87, v87
	s_nop 0
	v_mul_f32_e32 v141, 0x45800000, v87
	v_cndmask_b32_e32 v168, v87, v141, vcc
	v_mul_f32_e32 v87, 0x4b800000, v142
	v_cmp_gt_f32_e32 vcc, s17, v142
	v_pk_mul_f32 v[170:171], v[48:49], v[168:169] op_sel_hi:[1,0]
	v_pk_mul_f32 v[172:173], v[50:51], v[168:169] op_sel_hi:[1,0]
	v_cndmask_b32_e32 v87, v142, v87, vcc
	v_pk_mul_f32 v[170:171], v[4:5], v[170:171]
	v_pk_mul_f32 v[172:173], v[6:7], v[172:173]
	v_rsq_f32_e32 v87, v87
	v_cvt_pk_bf16_f32 v170, v170, v171
	v_cvt_pk_bf16_f32 v171, v172, v173
	global_store_dwordx2 v[158:159], v[170:171], off
	v_pk_mul_f32 v[170:171], v[52:53], v[168:169] op_sel_hi:[1,0]
	v_pk_mul_f32 v[172:173], v[54:55], v[168:169] op_sel_hi:[1,0]
	v_pk_mul_f32 v[170:171], v[16:17], v[170:171]
	v_pk_mul_f32 v[172:173], v[18:19], v[172:173]
	v_cvt_pk_bf16_f32 v170, v170, v171
	v_cvt_pk_bf16_f32 v171, v172, v173
	v_mul_f32_e32 v141, 0x45800000, v87
	global_store_dwordx2 v[158:159], v[170:171], off offset:512
	v_cndmask_b32_e32 v170, v87, v141, vcc
	v_pk_mul_f32 v[166:167], v[170:171], v[166:167] op_sel_hi:[0,1]
	v_pk_mul_f32 v[162:163], v[170:171], v[162:163] op_sel_hi:[0,1]
	v_pk_fma_f32 v[70:71], v[0:1], v[166:167], v[70:71]
	v_pk_fma_f32 v[74:75], v[8:9], v[162:163], v[74:75]
	v_pk_mul_f32 v[152:153], v[170:171], v[152:153] op_sel_hi:[0,1]
	v_pk_mul_f32 v[164:165], v[170:171], v[164:165] op_sel_hi:[0,1]
	v_pk_mul_f32 v[160:161], v[170:171], v[160:161] op_sel_hi:[0,1]
	v_pk_fma_f32 v[82:83], v[20:21], v[152:153], v[82:83]
	v_pk_mul_f32 v[150:151], v[170:171], v[150:151] op_sel_hi:[0,1]
	v_mov_b32_e32 v152, v75
	v_mov_b32_e32 v153, v71
	v_pk_fma_f32 v[72:73], v[2:3], v[164:165], v[72:73]
	v_pk_fma_f32 v[76:77], v[10:11], v[160:161], v[76:77]
	v_pk_mul_f32 v[156:157], v[170:171], v[156:157] op_sel_hi:[0,1]
	v_pk_fma_f32 v[84:85], v[22:23], v[150:151], v[84:85]
	v_mov_b32_e32 v150, v74
	v_mov_b32_e32 v151, v70
	v_pk_mul_f32 v[152:153], v[152:153], v[152:153]
	v_pk_fma_f32 v[78:79], v[12:13], v[156:157], v[78:79]
	v_pk_mul_f32 v[154:155], v[170:171], v[154:155] op_sel_hi:[0,1]
	v_pk_fma_f32 v[150:151], v[150:151], v[150:151], v[152:153]
	v_mov_b32_e32 v152, v76
	v_mov_b32_e32 v153, v72
	v_pk_fma_f32 v[80:81], v[14:15], v[154:155], v[80:81]
	v_pk_fma_f32 v[150:151], v[152:153], v[152:153], v[150:151]
	v_mov_b32_e32 v152, v77
	v_mov_b32_e32 v153, v73
	v_mov_b32_e32 v154, v83
	v_mov_b32_e32 v155, v79
	v_pk_fma_f32 v[150:151], v[152:153], v[152:153], v[150:151]
	v_mov_b32_e32 v152, v82
	v_mov_b32_e32 v153, v78
	v_pk_mul_f32 v[154:155], v[154:155], v[154:155]
	v_add_f32_e32 v87, v150, v151
	v_pk_fma_f32 v[152:153], v[152:153], v[152:153], v[154:155]
	v_mov_b32_e32 v154, v84
	v_mov_b32_e32 v155, v80
	v_pk_fma_f32 v[152:153], v[154:155], v[154:155], v[152:153]
	v_mov_b32_e32 v154, v85
	v_mov_b32_e32 v155, v81
	v_pk_fma_f32 v[152:153], v[154:155], v[154:155], v[152:153]
	v_pk_mul_f32 v[142:143], v[56:57], v[168:169] op_sel_hi:[1,0]
	v_add_f32_e32 v87, v153, v87
	v_add_f32_e32 v87, v152, v87
	ds_bpermute_b32 v141, v144, v87
	v_pk_mul_f32 v[150:151], v[58:59], v[168:169] op_sel_hi:[1,0]
	v_pk_mul_f32 v[142:143], v[24:25], v[142:143]
	v_pk_mul_f32 v[150:151], v[26:27], v[150:151]
	v_cvt_pk_bf16_f32 v142, v142, v143
	s_waitcnt lgkmcnt(0)
	v_add_f32_e32 v87, v87, v141
	ds_bpermute_b32 v141, v145, v87
	v_cvt_pk_bf16_f32 v143, v150, v151
	global_store_dwordx2 v[158:159], v[142:143], off offset:1024
	v_pk_mul_f32 v[142:143], v[60:61], v[168:169] op_sel_hi:[1,0]
	v_pk_mul_f32 v[150:151], v[62:63], v[168:169] op_sel_hi:[1,0]
	s_waitcnt lgkmcnt(0)
	v_add_f32_e32 v87, v87, v141
	ds_bpermute_b32 v141, v146, v87
	v_pk_mul_f32 v[142:143], v[28:29], v[142:143]
	v_pk_mul_f32 v[150:151], v[30:31], v[150:151]
	v_cvt_pk_bf16_f32 v142, v142, v143
	v_cvt_pk_bf16_f32 v143, v150, v151
	s_waitcnt lgkmcnt(0)
; __device__ __forceinline__ unsigned pk2(float lo, float hi) { const f32x2v v = {lo, hi}; const bf16x2v r = __builtin_convertvector(v, bf16x2v); return __builtin_bit_cast(unsigned, r); }
; __device__ __forceinline__ void rn_load(RowRegs& R, const float* hin32, const bf16_t* hin16, const bf16_t* f, int row, int lane) {
;   if (hin32) {
; #pragma unroll
;     for (int i = 0; i < 4; ++i) R.h[i] = *(const float4*)(hin32 + (size_t)row * 1024 + i * 256 + lane * 4);
;   } else {
; #pragma unroll
;     for (int i = 0; i < 4; ++i) { const u32x2 v = *(const u32x2*)(hin16 + (size_t)row * 1024 + i * 256 + lane * 4);
;       R.h[i].x = __uint_as_float(v.x << 16); R.h[i].y = __uint_as_float(v.x & 0xffff0000u); R.h[i].z = __uint_as_float(v.y << 16); R.h[i].w = __uint_as_float(v.y & 0xffff0000u); }
;   }
;   if (f) {
; #pragma unroll
;     for (int i = 0; i < 4; ++i) R.f[i] = *(const u32x2*)(f + (size_t)row * 1024 + i * 256 + lane * 4);
; __device__ __forceinline__ void rn_proc(RowRegs& R, float* hout32, bf16_t* hout16, bool has_f, float scale, const float4 (&gpo)[4], const float4 (&gpr)[4], bf16_t* a, int row, int lane) {
;     ...
;   if (a) {
;     float ss = 0.f;
; #pragma unroll
;     for (int i = 0; i < 4; ++i) ss += R.h[i].x * R.h[i].x + R.h[i].y * R.h[i].y + R.h[i].z * R.h[i].z + R.h[i].w * R.h[i].w;
;     ss = wave_sum(ss);
;     const float r = rsqrtf(ss * (1.f / 1024.f) + 1e-6f);
; #pragma unroll
;     for (int i = 0; i < 4; ++i) { const float4 g = gpr[i];
;       u32x2 o; o.x = pk2(R.h[i].x * r * g.x, R.h[i].y * r * g.y); o.y = pk2(R.h[i].z * r * g.z, R.h[i].w * r * g.w);
;       *(u32x2*)(a + (size_t)row * 1024 + i * 256 + lane * 4) = o; }
	v_add_f32_e32 v87, v87, v141
	ds_bpermute_b32 v153, v147, v87
	v_ashrrev_i32_e32 v141, 31, v140
	global_store_dwordx2 v[158:159], v[142:143], off offset:1536
	v_lshlrev_b64 v[142:143], 11, v[140:141]
	v_lshl_add_u64 v[150:151], v[64:65], 0, v[142:143]
	s_waitcnt lgkmcnt(0)
	v_add_f32_e32 v87, v87, v153
	ds_bpermute_b32 v141, v148, v87
	v_cvt_pk_bf16_f32 v152, v70, v71
	v_cvt_pk_bf16_f32 v153, v72, v73
	global_store_dwordx2 v[150:151], v[152:153], off
	v_cvt_pk_bf16_f32 v152, v74, v75
	s_waitcnt lgkmcnt(0)
	v_add_f32_e32 v87, v87, v141
	ds_bpermute_b32 v141, v149, v87
	v_cvt_pk_bf16_f32 v153, v76, v77
	global_store_dwordx2 v[150:151], v[152:153], off offset:512
	v_cvt_pk_bf16_f32 v152, v78, v79
	v_cvt_pk_bf16_f32 v153, v80, v81
	s_waitcnt lgkmcnt(0)
	v_add_f32_e32 v87, v87, v141
	v_fmamk_f32 v87, v87, 0x3a800000, v178
	v_mul_f32_e32 v141, 0x4b800000, v87
	v_cmp_gt_f32_e32 vcc, s17, v87
	global_store_dwordx2 v[150:151], v[152:153], off offset:1024
	v_cvt_pk_bf16_f32 v152, v82, v83
	v_cndmask_b32_e32 v87, v87, v141, vcc
	v_rsq_f32_e32 v87, v87
	v_cvt_pk_bf16_f32 v153, v84, v85
	global_store_dwordx2 v[150:151], v[152:153], off offset:1536
	v_lshl_add_u64 v[142:143], v[68:69], 0, v[142:143]
	v_mul_f32_e32 v141, 0x45800000, v87
	v_cndmask_b32_e32 v150, v87, v141, vcc
	v_pk_mul_f32 v[152:153], v[70:71], v[150:151] op_sel_hi:[1,0]
	v_pk_mul_f32 v[154:155], v[72:73], v[150:151] op_sel_hi:[1,0]
	v_pk_mul_f32 v[152:153], v[4:5], v[152:153]
	v_pk_mul_f32 v[154:155], v[6:7], v[154:155]
	v_cvt_pk_bf16_f32 v152, v152, v153
	v_cvt_pk_bf16_f32 v153, v154, v155
	global_store_dwordx2 v[142:143], v[152:153], off
	v_pk_mul_f32 v[152:153], v[74:75], v[150:151] op_sel_hi:[1,0]
	v_pk_mul_f32 v[154:155], v[76:77], v[150:151] op_sel_hi:[1,0]
	v_pk_mul_f32 v[152:153], v[16:17], v[152:153]
	v_pk_mul_f32 v[154:155], v[18:19], v[154:155]
	v_cvt_pk_bf16_f32 v152, v152, v153
	v_cvt_pk_bf16_f32 v153, v154, v155
	global_store_dwordx2 v[142:143], v[152:153], off offset:512
	v_pk_mul_f32 v[152:153], v[78:79], v[150:151] op_sel_hi:[1,0]
	v_pk_mul_f32 v[154:155], v[80:81], v[150:151] op_sel_hi:[1,0]
	v_pk_mul_f32 v[152:153], v[24:25], v[152:153]
	v_pk_mul_f32 v[154:155], v[26:27], v[154:155]
	v_cvt_pk_bf16_f32 v152, v152, v153
	v_cvt_pk_bf16_f32 v153, v154, v155
	global_store_dwordx2 v[142:143], v[152:153], off offset:1024
	v_pk_mul_f32 v[152:153], v[82:83], v[150:151] op_sel_hi:[1,0]
	v_pk_mul_f32 v[150:151], v[84:85], v[150:151] op_sel_hi:[1,0]
	v_pk_mul_f32 v[152:153], v[28:29], v[152:153]
	v_pk_mul_f32 v[150:151], v[30:31], v[150:151]
	v_cvt_pk_bf16_f32 v152, v152, v153
	v_cvt_pk_bf16_f32 v153, v150, v151
	v_cmp_gt_i32_e32 vcc, s16, v138
	global_store_dwordx2 v[142:143], v[152:153], off offset:1536
	s_and_saveexec_b64 s[30:31], vcc
	s_cbranch_execz .LBB0_130
	s_waitcnt vmcnt(16)
	v_lshlrev_b32_e32 v98, 16, v104
	v_and_b32_e32 v99, 0xffff0000, v104
	v_lshlrev_b32_e32 v104, 16, v105
	v_and_b32_e32 v105, 0xffff0000, v105
	v_lshlrev_b32_e32 v110, 16, v106
	v_and_b32_e32 v111, 0xffff0000, v106
	v_lshlrev_b32_e32 v114, 16, v107
	v_and_b32_e32 v115, 0xffff0000, v107
	v_lshlrev_b32_e32 v118, 16, v112
	v_and_b32_e32 v119, 0xffff0000, v112
	v_lshlrev_b32_e32 v122, 16, v113
	v_and_b32_e32 v123, 0xffff0000, v113
	v_lshlrev_b32_e32 v126, 16, v116
	v_and_b32_e32 v127, 0xffff0000, v116
	v_lshlrev_b32_e32 v130, 16, v117
	v_and_b32_e32 v131, 0xffff0000, v117
	v_lshlrev_b32_e32 v106, 16, v120
	v_and_b32_e32 v107, 0xffff0000, v120
	v_lshlrev_b32_e32 v112, 16, v121
	v_and_b32_e32 v113, 0xffff0000, v121
	v_lshlrev_b32_e32 v116, 16, v124
	v_and_b32_e32 v117, 0xffff0000, v124
	v_lshlrev_b32_e32 v120, 16, v125
	v_and_b32_e32 v121, 0xffff0000, v125
	v_lshlrev_b32_e32 v124, 16, v128
	v_and_b32_e32 v125, 0xffff0000, v128
	v_lshlrev_b32_e32 v128, 16, v129
	v_and_b32_e32 v129, 0xffff0000, v129
	v_lshlrev_b32_e32 v132, 16, v134
	v_and_b32_e32 v133, 0xffff0000, v134
	v_lshlrev_b32_e32 v134, 16, v135
	v_and_b32_e32 v135, 0xffff0000, v135
	v_readlane_b32 s16, v254, 36
	s_nop 1
	v_add_u32_e32 v142, s16, v86
	s_mov_b32 s16, 0x8000
	v_cmp_gt_i32_e32 vcc, s16, v142
	s_and_saveexec_b64 s[38:39], vcc
	s_cbranch_execz .LBB0_129
	s_mul_i32 s16, s92, 40
	v_add_u32_e32 v36, s16, v86
	v_ashrrev_i32_e32 v143, 31, v142
	v_ashrrev_i32_e32 v37, 31, v36
	v_lshlrev_b64 v[32:33], 11, v[142:143]
	v_lshlrev_b64 v[40:41], 11, v[36:37]
	v_lshl_add_u64 v[34:35], v[64:65], 0, v[32:33]
	v_lshl_add_u64 v[42:43], v[64:65], 0, v[40:41]
	global_load_dwordx2 v[50:51], v[34:35], off
	global_load_dwordx2 v[54:55], v[34:35], off offset:512
	global_load_dwordx2 v[58:59], v[34:35], off offset:1024
	global_load_dwordx2 v[62:63], v[34:35], off offset:1536
	global_load_dwordx2 v[72:73], v[42:43], off
	global_load_dwordx2 v[76:77], v[42:43], off offset:512
	v_lshl_add_u64 v[38:39], v[66:67], 0, v[32:33]
	v_lshl_add_u64 v[46:47], v[66:67], 0, v[40:41]
	global_load_dwordx2 v[80:81], v[42:43], off offset:1024
	global_load_dwordx2 v[32:33], v[38:39], off
	global_load_dwordx2 v[34:35], v[38:39], off offset:512
	global_load_dwordx2 v[36:37], v[38:39], off offset:1024
	s_nop 0
	global_load_dwordx2 v[38:39], v[38:39], off offset:1536
	s_nop 0
	global_load_dwordx2 v[84:85], v[42:43], off offset:1536
	global_load_dwordx2 v[40:41], v[46:47], off
	s_nop 0
	global_load_dwordx2 v[42:43], v[46:47], off offset:512
	global_load_dwordx2 v[44:45], v[46:47], off offset:1024
	s_nop 0
	global_load_dwordx2 v[46:47], v[46:47], off offset:1536
	s_branch .LBB0_129
